# wide u^T loads placed in hw0 slack + sample rebalance (m17_rebal760)
# speedup vs baseline: 1.0126x; 1.0054x over previous
.LBB0_919:
	s_add_i32 s28, s33, 0xffffff7b
	s_sub_i32 s4, 0x108, s33
	s_cmpk_lt_u32 s28, 0x83
	s_cselect_b32 s8, s4, 0
	s_sub_i32 s24, s3, s8
	s_cmp_ge_i32 s3, s8
	s_cselect_b32 s6, s24, 0x400
	s_cmpk_lt_i32 s6, 0x400
	s_cselect_b64 s[4:5], -1, 0
	s_movk_i32 s99, 0x400
	s_cmpk_lg_i32 s30, 0x100
	s_cbranch_scc1 .Lmy_samp_noovr
	s_cmpk_lt_u32 s2, 136
	s_cbranch_scc1 .Lmy_samp_bc
	s_sub_i32 s6, s2, 136
	s_movk_i32 s98, 120
	s_movk_i32 s99, 760
	s_branch .Lmy_samp_set
.Lmy_samp_bc:
	s_cmpk_lt_u32 s2, 64
	s_cbranch_scc1 .Lmy_samp_c
	s_sub_i32 s6, s2, 64
	s_addk_i32 s6, 760
	s_movk_i32 s98, 72
	s_movk_i32 s99, 1024
	s_branch .Lmy_samp_set
